# static s_setprio 1 for waves 0-3 (other half) through the GLA summary / attention / scan / GLA output phases
# speedup vs baseline: 1.0029x; 1.0029x over previous
; __device__ void phase_gla_summ(const P& p) {
;   int tid = opaque_tid(p);
;   int u = blockIdx.x;
;   if (u >= 4096) return;
;   SummRaw cur = gla_summ_load(p, u, tid);
;   for (; u < 4096; u += gridDim.x) {
;     int un = u + gridDim.x;
;     SummRaw nxt = gla_summ_load(p, un < 4096 ? un : u, tid);
.LBB0_222:
	s_or_b64 exec, exec, s[0:1]
	s_cmpk_lt_u32 s33, 0x100
	s_cbranch_scc0 .Lmy_prio_done
	s_setprio 1
